# attention main loops: K/V prefetch addresses as wave-uniform SGPR base (SALU-advanced) plus constant per-lane 32-bit offsets, removing 14 VALU and 7 s_nop of 64-bit address math per two KV tiles from
# speedup vs baseline: 1.0976x; 1.0217x over previous
.LBB0_422:
	s_lshl_b32 s0, s39, 10
	s_and_b32 s6, s0, 0x800000
	s_lshl_b32 s0, s43, 1
	s_and_b32 s66, s0, 0x300
	s_lshl_b32 s0, s64, 11
	s_lshl_b32 s1, s64, 4
	s_and_b32 s0, s0, 0x2000
	s_and_b32 s1, s1, 0xffffff80
	s_add_i32 s1, s0, s1
	v_or_b32_e32 v171, s1, v170
	v_or_b32_e32 v0, v171, v169
	v_ashrrev_i32_e32 v1, 31, v0
	s_lshl_b32 s1, s64, 7
	v_lshlrev_b64 v[0:1], 10, v[0:1]
	s_and_b32 s65, s1, 0x180
	v_lshl_add_u64 v[0:1], s[86:87], 0, v[0:1]
	s_lshl_b32 s4, s65, 1
	s_mov_b32 s5, s7
	v_lshl_add_u64 v[0:1], v[0:1], 0, s[4:5]
	s_lshl_b32 s5, s0, 10
	s_add_u32 s0, s33, s5
	s_addc_u32 s1, s34, 0
	s_add_u32 s0, s0, s4
	v_mov_b32_e32 v174, v168
	v_lshl_add_u64 v[0:1], v[160:161], 1, v[0:1]
	s_addc_u32 s1, s1, 0
	v_lshl_add_u64 v[0:1], v[0:1], 0, v[162:163]
	v_ashrrev_i32_e32 v16, 4, v174
	s_add_u32 s5, s35, s5
	v_lshlrev_b32_e32 v20, 3, v174
	v_add_u32_e32 v18, 32, v16
	s_addc_u32 s16, s38, 0
	global_load_dwordx4 v[124:127], v[0:1], off
	global_load_dwordx4 v[120:123], v[0:1], off offset:32
	global_load_dwordx4 v[116:119], v[0:1], off offset:64
	global_load_dwordx4 v[112:115], v[0:1], off offset:96
	v_and_b32_e32 v0, 0x78, v20
	v_ashrrev_i32_e32 v17, 31, v16
	v_ashrrev_i32_e32 v19, 31, v18
	s_add_u32 s4, s5, s4
	v_lshlrev_b32_e32 v21, 1, v0
	v_lshlrev_b64 v[48:49], 10, v[16:17]
	v_lshlrev_b64 v[12:13], 10, v[18:19]
	s_addc_u32 s5, s16, 0
	v_or_b32_e32 v50, v48, v21
	v_mov_b32_e32 v51, v49
	v_or_b32_e32 v12, v12, v21
	v_lshl_add_u64 v[0:1], s[4:5], 0, v[50:51]
	v_lshl_add_u64 v[4:5], s[4:5], 0, v[12:13]
	s_barrier
	global_load_dwordx4 v[0:3], v[0:1], off
	s_nop 0
	global_load_dwordx4 v[4:7], v[4:5], off
	v_lshl_add_u64 v[8:9], s[0:1], 0, v[50:51]
	global_load_dwordx4 v[8:11], v[8:9], off
	v_lshl_add_u64 v[12:13], s[0:1], 0, v[12:13]
	global_load_dwordx4 v[12:15], v[12:13], off
	v_and_b32_e32 v22, 0xfffff0, v16
	v_lshlrev_b32_e32 v23, 1, v16
	v_lshrrev_b32_e32 v24, 1, v16
	v_and_b32_e32 v25, 3, v16
	v_and_or_b32 v22, v23, 8, v22
	v_and_or_b32 v23, v24, 4, v25
	v_and_b32_e32 v24, 0xfffff0, v18
	v_lshlrev_b32_e32 v25, 1, v18
	v_and_b32_e32 v17, 0x70, v174
	v_bfe_u32 v20, v20, 5, 2
	v_lshlrev_b32_e32 v16, 8, v16
	v_lshrrev_b32_e32 v22, 1, v22
	v_and_or_b32 v24, v25, 8, v24
	v_bitop3_b32 v183, v21, v16, v17 bitop3:0xde
	v_or_b32_e32 v16, v22, v20
	v_lshrrev_b32_e32 v22, 1, v24
	v_lshlrev_b32_e32 v23, 6, v23
	v_and_b32_e32 v26, 48, v21
	v_lshlrev_b32_e32 v16, 9, v16
	v_or_b32_e32 v20, v22, v20
	v_or3_b32 v184, v16, v23, v26
	v_lshlrev_b32_e32 v16, 9, v20
	v_bfe_u32 v172, v174, 5, 1
	v_ashrrev_i32_e32 v175, 8, v174
	v_lshlrev_b32_e32 v52, 4, v174
	v_or3_b32 v186, v16, v23, v26
	v_add_u32_e32 v84, 16, v184
	v_and_b32_e32 v173, 31, v174
	v_lshlrev_b32_e32 v19, 7, v175
	v_add_u32_e32 v24, 16, v183
	v_add_u32_e32 v85, 16, v186
	s_waitcnt vmcnt(0)
	v_lshlrev_b32_e32 v176, 4, v172
	v_lshlrev_b32_e32 v190, 8, v173
	v_and_b32_e32 v86, 63, v174
	v_lshl_add_u64 v[60:61], v[50:51], 0, s[14:15]
	v_lshl_add_u64 v[64:65], v[50:51], 0, s[36:37]
	v_lshl_add_u64 v[56:57], s[4:5], 0, v[64:65]
	v_lshl_add_u64 v[64:65], s[0:1], 0, v[64:65]
	s_cmp_lg_u32 16, -1
	s_cselect_b32 s16, 16, 0
	s_mov_b32 s17, s7
	s_mov_b32 s18, s7
	s_mov_b32 s19, s7
	s_mov_b32 s20, s7
	s_waitcnt vmcnt(3)
	ds_write_b128 v84, v[0:3]
	s_waitcnt vmcnt(2)
	ds_write_b128 v85, v[4:7]
	s_waitcnt vmcnt(1)
	ds_write_b128 v24, v[8:11] offset:49152
	v_and_b32_e32 v8, 0x70, v52
	v_lshlrev_b32_e32 v0, 8, v18
	v_bitop3_b32 v182, v176, v8, v19 bitop3:0x36
	v_bitop3_b32 v188, v21, v0, v17 bitop3:0xde
	v_add_u32_e32 v185, v182, v190
	v_add_u32_e32 v0, 16, v188
	v_add_u32_e32 v4, 16, v185
	s_waitcnt vmcnt(0)
	ds_write_b128 v0, v[12:15] offset:49152
	s_waitcnt lgkmcnt(0)
	s_barrier
	ds_read_b128 v[0:3], v4 offset:49152
	ds_read_b128 v[4:7], v4 offset:57344
	v_or_b32_e32 v9, v176, v19
	v_bitop3_b32 v187, v9, v8, 32 bitop3:0x36
	v_add_u32_e32 v189, v187, v190
	s_waitcnt lgkmcnt(0)
	v_mfma_f32_32x32x16_bf16 v[16:31], v[4:7], v[124:127], 0
	v_add_u32_e32 v4, 16, v189
	v_bitop3_b32 v193, v9, v8, s3 bitop3:0x36
	v_bitop3_b32 v191, v9, v8, 64 bitop3:0x36
	v_add_u32_e32 v194, v193, v190
	v_add_u32_e32 v192, v191, v190
	v_add_u32_e32 v8, 16, v194
	v_and_b32_e32 v5, 0x3fffffc0, v174
	v_mfma_f32_32x32x16_bf16 v[32:47], v[0:3], v[124:127], 0
	ds_read_b128 v[0:3], v4 offset:49152
	v_and_b32_e32 v11, 0xc0, v52
	v_add_u32_e32 v13, 16, v192
	ds_read_b128 v[52:55], v8 offset:57344
	v_lshl_add_u32 v177, v5, 2, s50
	ds_read_b128 v[4:7], v4 offset:57344
	v_lshlrev_b32_e32 v10, 3, v86
	s_waitcnt lgkmcnt(2)
	v_mfma_f32_32x32x16_bf16 v[32:47], v[0:3], v[120:123], v[32:47]
	v_lshlrev_b32_e32 v0, 1, v174
	v_and_b32_e32 v12, 32, v0
	ds_read_b128 v[0:3], v13 offset:49152
	v_and_or_b32 v11, v10, 24, v11
	s_mov_b32 s21, s7
	s_mov_b32 s22, s7
	s_mov_b32 s23, s7
	s_waitcnt lgkmcnt(0)
	v_mfma_f32_32x32x16_bf16 v[32:47], v[0:3], v[116:119], v[32:47]
	ds_read_b128 v[0:3], v8 offset:49152
	s_mov_b32 s24, s7
	s_mov_b32 s25, s7
	s_mov_b32 s26, s7
	s_mov_b32 s27, s7
	s_mov_b32 s28, s7
	s_mov_b32 s29, s7
	v_mfma_f32_32x32x16_bf16 v[16:31], v[4:7], v[120:123], v[16:31]
	v_and_b32_e32 v4, 0x100, v10
	v_or3_b32 v178, v11, v12, v4
	ds_read_b128 v[4:7], v13 offset:57344
	v_add_u32_e32 v181, s16, v178
	s_mov_b32 s16, s7
	s_mov_b32 s30, s7
	s_mov_b32 s31, s7
	s_waitcnt lgkmcnt(0)
	v_mfma_f32_32x32x16_bf16 v[16:31], v[4:7], v[116:119], v[16:31]
	v_lshl_add_u32 v179, v173, 2, v177
	v_mov_b32_e32 v196, 1.0
	v_mov_b32_e32 v180, 0
	v_mfma_f32_32x32x16_bf16 v[32:47], v[0:3], v[112:115], v[32:47]
	v_mov_b64_e32 v[0:1], s[16:17]
	v_mov_b64_e32 v[14:15], s[30:31]
	v_mov_b64_e32 v[2:3], s[18:19]
	v_mov_b64_e32 v[4:5], s[20:21]
	v_mov_b64_e32 v[6:7], s[22:23]
	v_mov_b64_e32 v[8:9], s[24:25]
	v_mov_b64_e32 v[10:11], s[26:27]
	v_mfma_f32_32x32x16_bf16 v[16:31], v[52:55], v[112:115], v[16:31]
	s_nop 3
	v_max_f32_e32 v52, v33, v33
	v_max_f32_e32 v53, v32, v32
	v_max_f32_e32 v52, v53, v52
	v_max3_f32 v52, v52, v34, v35
	v_max3_f32 v52, v52, v36, v37
	v_max3_f32 v52, v52, v38, v39
	v_max3_f32 v52, v52, v40, v41
	v_max3_f32 v52, v52, v42, v43
	v_max3_f32 v52, v52, v44, v45
	v_max3_f32 v66, v52, v46, v47
	v_lshl_add_u64 v[52:53], s[4:5], 0, v[60:61]
	v_lshl_add_u64 v[60:61], s[0:1], 0, v[60:61]
	global_load_dwordx4 v[52:55], v[52:53], off
	s_nop 0
	global_load_dwordx4 v[56:59], v[56:57], off
	v_mov_b64_e32 v[12:13], s[28:29]
	global_load_dwordx4 v[60:63], v[60:61], off
	s_mov_b32 s19, 1
	global_load_dwordx4 v[80:83], v[64:65], off
	v_max3_f32 v64, v66, v16, v17
	v_max3_f32 v64, v64, v18, v19
	v_max3_f32 v64, v64, v20, v21
	v_max3_f32 v64, v64, v22, v23
	v_max3_f32 v64, v64, v24, v25
	v_max3_f32 v64, v64, v26, v27
	v_max3_f32 v64, v64, v28, v29
	v_max3_f32 v70, v64, v30, v31
	v_lshl_add_u64 v[64:65], v[50:51], 0, s[40:41]
	v_lshl_add_u64 v[66:67], s[0:1], 0, v[64:65]
	v_lshl_add_u64 v[50:51], v[50:51], 0, s[44:45]
	v_lshl_add_u64 v[64:65], s[4:5], 0, v[64:65]
	v_lshl_add_u64 v[68:69], s[0:1], 0, v[50:51]
	global_load_dwordx4 v[136:139], v[66:67], off
	global_load_dwordx4 v[128:131], v[68:69], off
	v_lshl_add_u64 v[50:51], s[4:5], 0, v[50:51]
	global_load_dwordx4 v[140:143], v[64:65], off
	global_load_dwordx4 v[132:135], v[50:51], off
	v_mov_b32_e32 v71, v70
	s_nop 1
	v_permlane32_swap_b32_e32 v70, v71
	v_max_f32_e32 v50, v71, v71
	v_max_f32_e32 v51, v70, v70
	v_max_f32_e32 v50, v51, v50
	v_sub_f32_e32 v64, v16, v50
	v_add_u32_e32 v16, s58, v183
	v_sub_f32_e32 v32, v32, v50
	v_sub_f32_e32 v33, v33, v50
	v_sub_f32_e32 v34, v34, v50
	v_sub_f32_e32 v35, v35, v50
	v_sub_f32_e32 v36, v36, v50
	v_sub_f32_e32 v37, v37, v50
	v_sub_f32_e32 v38, v38, v50
	v_sub_f32_e32 v39, v39, v50
	v_sub_f32_e32 v40, v40, v50
	v_sub_f32_e32 v41, v41, v50
	v_sub_f32_e32 v42, v42, v50
	v_sub_f32_e32 v43, v43, v50
	v_sub_f32_e32 v44, v44, v50
	v_sub_f32_e32 v45, v45, v50
	v_sub_f32_e32 v46, v46, v50
	v_sub_f32_e32 v47, v47, v50
	v_sub_f32_e32 v66, v18, v50
	s_waitcnt vmcnt(4)
	s_waitcnt vmcnt(7)
	ds_write_b128 v84, v[52:55] offset:16384
	s_waitcnt vmcnt(6)
	ds_write_b128 v85, v[56:59] offset:16384
	v_and_b32_e32 v18, 15, v174
	s_waitcnt vmcnt(5)
	ds_write_b128 v16, v[60:63]
	v_add_u32_e32 v16, s58, v188
	v_sub_f32_e32 v65, v17, v50
	v_exp_f32_e32 v152, v32
	v_exp_f32_e32 v153, v33
	v_exp_f32_e32 v154, v34
	v_exp_f32_e32 v155, v35
	v_exp_f32_e32 v156, v36
	v_exp_f32_e32 v157, v37
	v_exp_f32_e32 v158, v38
	v_exp_f32_e32 v159, v39
	v_exp_f32_e32 v144, v40
	v_exp_f32_e32 v145, v41
	v_exp_f32_e32 v146, v42
	v_exp_f32_e32 v147, v43
	v_exp_f32_e32 v148, v44
	v_exp_f32_e32 v149, v45
	v_exp_f32_e32 v150, v46
	v_exp_f32_e32 v151, v47
	s_waitcnt vmcnt(4)
	ds_write_b128 v16, v[80:83]
	v_lshl_add_u64 v[16:17], s[6:7], 0, v[48:49]
	v_lshlrev_b32_e32 v18, 4, v18
	v_or3_b32 v16, v16, s66, v18
	v_add_f32_e32 v195, 0, v50
	v_sub_f32_e32 v79, v31, v50
	v_sub_f32_e32 v78, v30, v50
	v_sub_f32_e32 v77, v29, v50
	v_sub_f32_e32 v76, v28, v50
	v_sub_f32_e32 v75, v27, v50
	v_sub_f32_e32 v74, v26, v50
	v_sub_f32_e32 v73, v25, v50
	v_sub_f32_e32 v72, v24, v50
	v_sub_f32_e32 v71, v23, v50
	v_sub_f32_e32 v70, v22, v50
	v_sub_f32_e32 v69, v21, v50
	v_sub_f32_e32 v68, v20, v50
	v_sub_f32_e32 v67, v19, v50
	v_lshl_add_u64 v[166:167], s[12:13], 0, v[16:17]
	v_mov_b64_e32 v[62:63], v[14:15]
	v_mov_b64_e32 v[46:47], v[14:15]
	v_mov_b64_e32 v[30:31], v[14:15]
	v_cmp_gt_u32_e64 s[0:1], 32, v86
	v_mov_b64_e32 v[60:61], v[12:13]
	v_mov_b64_e32 v[58:59], v[10:11]
	v_mov_b64_e32 v[56:57], v[8:9]
	v_mov_b64_e32 v[54:55], v[6:7]
	v_mov_b64_e32 v[52:53], v[4:5]
	v_mov_b64_e32 v[50:51], v[2:3]
	v_mov_b64_e32 v[48:49], v[0:1]
	v_mov_b64_e32 v[44:45], v[12:13]
	v_mov_b64_e32 v[42:43], v[10:11]
	v_mov_b64_e32 v[40:41], v[8:9]
	v_mov_b64_e32 v[38:39], v[6:7]
	v_mov_b64_e32 v[36:37], v[4:5]
	v_mov_b64_e32 v[34:35], v[2:3]
	v_mov_b64_e32 v[32:33], v[0:1]
	v_mov_b64_e32 v[28:29], v[12:13]
	v_mov_b64_e32 v[26:27], v[10:11]
	v_mov_b64_e32 v[24:25], v[8:9]
	v_mov_b64_e32 v[22:23], v[6:7]
	v_mov_b64_e32 v[20:21], v[4:5]
	v_mov_b64_e32 v[18:19], v[2:3]
	v_mov_b64_e32 v[16:17], v[0:1]
	s_mov_b32 s6, 1
	s_mov_b32 s18, 0
	s_waitcnt lgkmcnt(0)
	s_barrier
	v_add_co_u32_e32 v242, vcc, s61, v166
	s_nop 1
	v_addc_co_u32_e32 v243, vcc, -1, v167, vcc
	s_nop 0
	v_readfirstlane_b32 s98, v242
	v_readfirstlane_b32 s99, v243
	s_nop 1
	v_subrev_u32_e32 v242, s98, v242
	v_add_u32_e32 v243, 0x8000, v242
	v_add_u32_e32 v244, 0x1000000, v242
	v_add_u32_e32 v245, 0x1008000, v242
.LBB0_423:
	s_lshl_b32 s16, s19, 14
	s_add_i32 s4, s16, 16
	v_add_u32_e32 v96, s4, v185
	ds_read_b128 v[198:201], v96 offset:49152
	ds_read_b128 v[202:205], v96 offset:57344
	v_xor_b32_e32 v80, 0x80000000, v195
	v_mov_b32_e32 v81, v80
	v_mov_b32_e32 v82, v80
	v_mov_b32_e32 v83, v80
	v_mov_b32_e32 v84, v80
	v_mov_b32_e32 v85, v80
	v_mov_b32_e32 v86, v80
	v_mov_b32_e32 v87, v80
	v_mov_b32_e32 v88, v80
	v_mov_b32_e32 v89, v80
	v_mov_b32_e32 v90, v80
	v_mov_b32_e32 v91, v80
	v_mov_b32_e32 v92, v80
	v_mov_b32_e32 v93, v80
	v_mov_b32_e32 v94, v80
	v_mov_b32_e32 v95, v80
	v_exp_f32_e32 v221, v64
	v_add_f32_e32 v64, 0, v152
	s_waitcnt lgkmcnt(1)
	v_mfma_f32_32x32x16_bf16 v[96:111], v[198:201], v[124:127], v[80:95]
	v_add_f32_e32 v64, v153, v64
	v_add_f32_e32 v64, v154, v64
	v_add_u32_e32 v197, s4, v189
	v_add_f32_e32 v64, v155, v64
	v_add_f32_e32 v64, v156, v64
	v_add_f32_e32 v64, v157, v64
	v_add_f32_e32 v64, v158, v64
	s_waitcnt lgkmcnt(0)
	v_mfma_f32_32x32x16_bf16 v[80:95], v[202:205], v[124:127], v[80:95]
	ds_read_b128 v[198:201], v197 offset:49152
	ds_read_b128 v[202:205], v197 offset:57344
	v_add_f32_e32 v64, v159, v64
	v_add_f32_e32 v64, v144, v64
	v_add_f32_e32 v64, v145, v64
	v_add_f32_e32 v64, v146, v64
	v_add_u32_e32 v197, s4, v192
	v_add_f32_e32 v64, v147, v64
	s_waitcnt lgkmcnt(1)
	v_mfma_f32_32x32x16_bf16 v[96:111], v[198:201], v[120:123], v[96:111]
	ds_read_b128 v[198:201], v197 offset:49152
	ds_read_b128 v[206:209], v197 offset:57344
	v_add_f32_e32 v64, v148, v64
	v_exp_f32_e32 v222, v65
	v_add_f32_e32 v64, v149, v64
	v_exp_f32_e32 v223, v66
	v_add_f32_e32 v64, v150, v64
	v_exp_f32_e32 v224, v67
	s_waitcnt lgkmcnt(2)
	v_mfma_f32_32x32x16_bf16 v[80:95], v[202:205], v[120:123], v[80:95]
	v_add_f32_e32 v64, v151, v64
	v_add_f32_e32 v64, v221, v64
	v_add_f32_e32 v64, v222, v64
	v_add_f32_e32 v64, v223, v64
	v_exp_f32_e32 v71, v71
	v_add_f32_e32 v64, v224, v64
	v_add_u32_e32 v197, s4, v194
	s_waitcnt lgkmcnt(1)
	v_mfma_f32_32x32x16_bf16 v[96:111], v[198:201], v[116:119], v[96:111]
	v_exp_f32_e32 v199, v68
	v_exp_f32_e32 v200, v69
	v_exp_f32_e32 v201, v70
	v_exp_f32_e32 v225, v72
	v_add_f32_e32 v64, v199, v64
	ds_read_b128 v[202:205], v197 offset:49152
	ds_read_b128 v[210:213], v197 offset:57344
	v_exp_f32_e32 v226, v73
	s_waitcnt lgkmcnt(2)
	v_mfma_f32_32x32x16_bf16 v[80:95], v[206:209], v[116:119], v[80:95]
	v_add_f32_e32 v64, v200, v64
	v_exp_f32_e32 v227, v74
	v_add_f32_e32 v64, v201, v64
	v_exp_f32_e32 v206, v75
	v_add_f32_e32 v64, v71, v64
	v_exp_f32_e32 v207, v76
	v_add_f32_e32 v64, v225, v64
	v_exp_f32_e32 v208, v77
	v_add_f32_e32 v64, v226, v64
	v_exp_f32_e32 v209, v78
	s_waitcnt lgkmcnt(1)
	v_mfma_f32_32x32x16_bf16 v[96:111], v[202:205], v[112:115], v[96:111]
	v_add_f32_e32 v64, v227, v64
	v_exp_f32_e32 v79, v79
	v_add_f32_e32 v64, v206, v64
	v_add_f32_e32 v64, v207, v64
	v_add_f32_e32 v64, v208, v64
	v_add_f32_e32 v64, v209, v64
	v_add_f32_e32 v197, v79, v64
	s_waitcnt lgkmcnt(0)
	v_mfma_f32_32x32x16_bf16 v[80:95], v[210:213], v[112:115], v[80:95]
	v_mov_b32_e32 v198, v197
	v_cvt_pk_bf16_f32 v64, v152, v153
	v_cvt_pk_bf16_f32 v65, v154, v155
	v_cvt_pk_bf16_f32 v66, v156, v157
	v_cvt_pk_bf16_f32 v67, v158, v159
	v_cvt_pk_bf16_f32 v72, v144, v145
	v_cvt_pk_bf16_f32 v73, v146, v147
	v_cvt_pk_bf16_f32 v74, v148, v149
	v_cvt_pk_bf16_f32 v75, v150, v151
	v_cvt_pk_bf16_f32 v68, v221, v222
	v_cvt_pk_bf16_f32 v69, v223, v224
	v_cvt_pk_bf16_f32 v70, v199, v200
	v_cvt_pk_bf16_f32 v71, v201, v71
	v_cvt_pk_bf16_f32 v76, v225, v226
	v_cvt_pk_bf16_f32 v77, v227, v206
	v_cvt_pk_bf16_f32 v78, v207, v208
	v_cvt_pk_bf16_f32 v79, v209, v79
	v_permlane32_swap_b32_e32 v197, v198
	v_permlane32_swap_b32_e32 v64, v66
	v_permlane32_swap_b32_e32 v65, v67
	v_permlane32_swap_b32_e32 v72, v74
	v_permlane32_swap_b32_e32 v73, v75
	v_permlane32_swap_b32_e32 v68, v70
	v_permlane32_swap_b32_e32 v69, v71
	v_permlane32_swap_b32_e32 v76, v78
	v_permlane32_swap_b32_e32 v77, v79
	global_load_dwordx4 v[144:147], v244, s[98:99]
	global_load_dwordx4 v[148:151], v245, s[98:99]
	global_load_dwordx4 v[152:155], v242, s[98:99]
	global_load_dwordx4 v[156:159], v243, s[98:99]
	s_add_u32 s98, s98, 0x10000
	s_addc_u32 s99, s99, 0
	v_lshl_add_u32 v199, s18, 14, v181
	ds_read_b64_tr_b16 v[200:201], v199 offset:0
	ds_read_b64_tr_b16 v[202:203], v199 offset:0x800
	ds_read_b64_tr_b16 v[204:205], v199 offset:0x1000
	ds_read_b64_tr_b16 v[206:207], v199 offset:0x1800
	ds_read_b64_tr_b16 v[208:209], v199 offset:0x2000
	ds_read_b64_tr_b16 v[210:211], v199 offset:0x2800
	ds_read_b64_tr_b16 v[222:223], v199 offset:0x3000
	ds_read_b64_tr_b16 v[224:225], v199 offset:0x3800
	s_waitcnt lgkmcnt(0)
	s_nop 0
	v_mfma_f32_32x32x16_bf16 v[0:15], v[64:67], v[200:203], v[0:15]
	v_max_f32_e32 v200, v97, v97
	v_max_f32_e32 v201, v96, v96
	v_max_f32_e32 v200, v201, v200
	v_max3_f32 v200, v200, v98, v99
	v_max3_f32 v200, v200, v100, v101
	v_max3_f32 v200, v200, v102, v103
	v_max3_f32 v200, v200, v104, v105
	v_mfma_f32_32x32x16_bf16 v[0:15], v[72:75], v[204:207], v[0:15]
	v_max3_f32 v200, v200, v106, v107
	v_max3_f32 v202, v200, v108, v109
	ds_read_b64_tr_b16 v[200:201], v199 offset:0x200
	v_max3_f32 v212, v202, v110, v111
	ds_read_b64_tr_b16 v[202:203], v199 offset:0xa00
	ds_read_b64_tr_b16 v[204:205], v199 offset:0x1200
	ds_read_b64_tr_b16 v[206:207], v199 offset:0x1a00
	v_mfma_f32_32x32x16_bf16 v[0:15], v[68:71], v[208:211], v[0:15]
	ds_read_b64_tr_b16 v[208:209], v199 offset:0x2200
	ds_read_b64_tr_b16 v[210:211], v199 offset:0x2a00
	ds_read_b64_tr_b16 v[226:227], v199 offset:0x3200
	ds_read_b64_tr_b16 v[228:229], v199 offset:0x3a00
	s_waitcnt lgkmcnt(0)
	v_mfma_f32_32x32x16_bf16 v[0:15], v[76:79], v[222:225], v[0:15]
	v_mfma_f32_32x32x16_bf16 v[48:63], v[64:67], v[200:203], v[48:63]
	v_max3_f32 v212, v212, v80, v81
	v_max3_f32 v200, v212, v82, v83
	ds_read_b64_tr_b16 v[202:203], v199 offset:0x400
	v_max3_f32 v200, v200, v84, v85
	v_max3_f32 v200, v200, v86, v87
	v_max3_f32 v200, v200, v88, v89
	v_max3_f32 v200, v200, v90, v91
	v_mfma_f32_32x32x16_bf16 v[48:63], v[72:75], v[204:207], v[48:63]
	ds_read_b64_tr_b16 v[204:205], v199 offset:0xc00
	ds_read_b64_tr_b16 v[206:207], v199 offset:0x1400
	v_max3_f32 v200, v200, v92, v93
	v_max3_f32 v200, v200, v94, v95
	v_mov_b32_e32 v201, v200
	s_nop 1
	v_permlane32_swap_b32_e32 v200, v201
	v_mfma_f32_32x32x16_bf16 v[48:63], v[68:71], v[208:211], v[48:63]
	ds_read_b64_tr_b16 v[208:209], v199 offset:0x1c00
	ds_read_b64_tr_b16 v[210:211], v199 offset:0x2400
	ds_read_b64_tr_b16 v[212:213], v199 offset:0x2c00
	ds_read_b64_tr_b16 v[222:223], v199 offset:0x3400
	ds_read_b64_tr_b16 v[224:225], v199 offset:0x3c00
	s_waitcnt lgkmcnt(0)
	v_max_f32_e32 v201, v201, v201
	v_mfma_f32_32x32x16_bf16 v[48:63], v[76:79], v[226:229], v[48:63]
	v_max_f32_e32 v200, v200, v200
	v_max_f32_e32 v200, v200, v201
	v_mfma_f32_32x32x16_bf16 v[32:47], v[64:67], v[202:205], v[32:47]
	v_cmp_ge_f32_e32 vcc, s63, v200
	s_cmp_eq_u64 vcc, exec
	v_mfma_f32_32x32x16_bf16 v[32:47], v[72:75], v[206:209], v[32:47]
	v_mfma_f32_32x32x16_bf16 v[32:47], v[68:71], v[210:213], v[32:47]
	v_mfma_f32_32x32x16_bf16 v[32:47], v[76:79], v[222:225], v[32:47]
	s_cbranch_scc0 .LBB0_438
	v_mov_b32_e32 v200, 1.0

.LBB0_429:
	v_exp_f32_e32 v199, v96
	v_exp_f32_e32 v221, v97
	v_exp_f32_e32 v226, v98
	v_exp_f32_e32 v227, v99
	v_exp_f32_e32 v228, v100
	v_exp_f32_e32 v229, v101
	v_exp_f32_e32 v230, v102
	v_exp_f32_e32 v231, v103
	v_exp_f32_e32 v232, v104
	v_exp_f32_e32 v233, v105
	v_exp_f32_e32 v234, v106
	v_exp_f32_e32 v235, v107
	v_exp_f32_e32 v236, v108
	v_exp_f32_e32 v237, v109
	v_exp_f32_e32 v238, v110
	v_exp_f32_e32 v239, v111
	s_waitcnt lgkmcnt(0)
	s_barrier
	v_add_u32_e32 v96, s17, v185
	ds_read_b128 v[202:205], v96 offset:49152
	ds_read_b128 v[206:209], v96 offset:57344
	v_xor_b32_e32 v64, 0x80000000, v195
	v_mov_b32_e32 v65, v64
	v_mov_b32_e32 v66, v64
	v_mov_b32_e32 v67, v64
	v_mov_b32_e32 v68, v64
	v_mov_b32_e32 v69, v64
	v_mov_b32_e32 v70, v64
	v_mov_b32_e32 v71, v64
	v_mov_b32_e32 v72, v64
	v_mov_b32_e32 v73, v64
	v_mov_b32_e32 v74, v64
	v_mov_b32_e32 v75, v64
	v_mov_b32_e32 v76, v64
	v_mov_b32_e32 v77, v64
	v_mov_b32_e32 v78, v64
	v_mov_b32_e32 v79, v64
	v_add_u32_e32 v201, s17, v189
	v_exp_f32_e32 v80, v80
	s_waitcnt lgkmcnt(1)
	v_mfma_f32_32x32x16_bf16 v[96:111], v[202:205], v[124:127], v[64:79]
	v_exp_f32_e32 v81, v81
	v_exp_f32_e32 v82, v82
	v_exp_f32_e32 v83, v83
	v_exp_f32_e32 v84, v84
	v_exp_f32_e32 v85, v85
	v_exp_f32_e32 v86, v86
	v_exp_f32_e32 v87, v87
	s_waitcnt lgkmcnt(0)
	v_mfma_f32_32x32x16_bf16 v[64:79], v[206:209], v[124:127], v[64:79]
	ds_read_b128 v[202:205], v201 offset:49152
	ds_read_b128 v[206:209], v201 offset:57344
	v_add_u32_e32 v201, s17, v192
	v_exp_f32_e32 v240, v91
	v_exp_f32_e32 v241, v92
	v_cvt_pk_bf16_f32 v91, v230, v231
	v_cvt_pk_bf16_f32 v92, v232, v233
	s_waitcnt lgkmcnt(1)
	v_mfma_f32_32x32x16_bf16 v[96:111], v[202:205], v[120:123], v[96:111]
	ds_read_b128 v[202:205], v201 offset:49152
	ds_read_b128 v[210:213], v201 offset:57344
	v_add_u32_e32 v201, s17, v194
	s_waitcnt lgkmcnt(1)
	v_mfma_f32_32x32x16_bf16 v[96:111], v[202:205], v[116:119], v[96:111]
	v_exp_f32_e32 v203, v88
	v_add_f32_e32 v88, 0, v199
	v_add_f32_e32 v88, v221, v88
	v_add_f32_e32 v88, v226, v88
	v_add_f32_e32 v88, v227, v88
	v_add_f32_e32 v88, v228, v88
	v_add_f32_e32 v88, v229, v88
	v_add_f32_e32 v88, v230, v88
	v_add_f32_e32 v88, v231, v88
	v_add_f32_e32 v88, v232, v88
	v_add_f32_e32 v88, v233, v88
	v_mfma_f32_32x32x16_bf16 v[64:79], v[206:209], v[120:123], v[64:79]
	v_add_f32_e32 v88, v234, v88
	v_add_f32_e32 v88, v235, v88
	v_add_f32_e32 v88, v236, v88
	v_add_f32_e32 v88, v237, v88
	v_add_f32_e32 v88, v238, v88
	v_add_f32_e32 v88, v239, v88
	v_add_f32_e32 v88, v80, v88
	v_add_f32_e32 v88, v81, v88
	s_waitcnt lgkmcnt(0)
	v_mfma_f32_32x32x16_bf16 v[64:79], v[210:213], v[116:119], v[64:79]
	v_add_f32_e32 v88, v82, v88
	v_add_f32_e32 v88, v83, v88
	v_add_f32_e32 v88, v84, v88
	ds_read_b128 v[206:209], v201 offset:49152
	ds_read_b128 v[222:225], v201 offset:57344
	v_exp_f32_e32 v204, v89
	v_add_f32_e32 v88, v85, v88
	v_exp_f32_e32 v205, v90
	v_add_f32_e32 v88, v86, v88
	v_add_f32_e32 v88, v87, v88
	v_add_f32_e32 v88, v203, v88
	v_exp_f32_e32 v210, v93
	v_add_f32_e32 v88, v204, v88
	v_exp_f32_e32 v211, v94
	s_waitcnt lgkmcnt(1)
	v_mfma_f32_32x32x16_bf16 v[96:111], v[206:209], v[112:115], v[96:111]
	v_add_f32_e32 v88, v205, v88
	v_exp_f32_e32 v212, v95
	v_add_f32_e32 v88, v240, v88
	v_add_f32_e32 v88, v241, v88
	v_add_f32_e32 v88, v210, v88
	v_add_f32_e32 v88, v211, v88
	v_add_f32_e32 v201, v212, v88
	s_waitcnt lgkmcnt(0)
	v_mfma_f32_32x32x16_bf16 v[64:79], v[222:225], v[112:115], v[64:79]
	v_mov_b32_e32 v202, v201
	v_cvt_pk_bf16_f32 v88, v199, v221
	v_cvt_pk_bf16_f32 v89, v226, v227
	v_cvt_pk_bf16_f32 v90, v228, v229
	v_cvt_pk_bf16_f32 v93, v234, v235
	v_cvt_pk_bf16_f32 v94, v236, v237
	v_cvt_pk_bf16_f32 v95, v238, v239
	v_cvt_pk_bf16_f32 v80, v80, v81
	v_cvt_pk_bf16_f32 v81, v82, v83
	v_cvt_pk_bf16_f32 v82, v84, v85
	v_cvt_pk_bf16_f32 v83, v86, v87
	v_cvt_pk_bf16_f32 v84, v203, v204
	v_cvt_pk_bf16_f32 v85, v205, v240
	v_cvt_pk_bf16_f32 v86, v241, v210
	v_cvt_pk_bf16_f32 v87, v211, v212
	v_permlane32_swap_b32_e32 v201, v202
	v_permlane32_swap_b32_e32 v88, v90
	v_permlane32_swap_b32_e32 v89, v91
	v_permlane32_swap_b32_e32 v92, v94
	v_permlane32_swap_b32_e32 v93, v95
	v_permlane32_swap_b32_e32 v80, v82
	v_permlane32_swap_b32_e32 v81, v83
	v_permlane32_swap_b32_e32 v84, v86
	v_permlane32_swap_b32_e32 v85, v87
	s_cmpk_gt_u32 s6, 0x7c
	s_cselect_b64 s[4:5], -1, 0
	s_and_b64 vcc, exec, s[4:5]
	s_cbranch_vccnz .LBB0_431
	global_load_dwordx4 v[132:135], v244, s[98:99]
	global_load_dwordx4 v[128:131], v242, s[98:99]
	global_load_dwordx4 v[140:143], v245, s[98:99]
	global_load_dwordx4 v[136:139], v243, s[98:99]
	s_add_u32 s98, s98, 0x10000
	s_addc_u32 s99, s99, 0

.LBB0_436:
	v_exp_f32_e32 v152, v96
	v_exp_f32_e32 v153, v97
	v_exp_f32_e32 v154, v98
	v_exp_f32_e32 v155, v99
	v_exp_f32_e32 v156, v100
	v_exp_f32_e32 v157, v101
	v_exp_f32_e32 v158, v102
	v_exp_f32_e32 v159, v103
	v_exp_f32_e32 v144, v104
	v_exp_f32_e32 v145, v105
	v_exp_f32_e32 v146, v106
	v_exp_f32_e32 v147, v107
	v_exp_f32_e32 v148, v108
	v_exp_f32_e32 v149, v109
	v_exp_f32_e32 v150, v110
	v_exp_f32_e32 v151, v111
	v_add_f32_e32 v80, v197, v198
	v_fmac_f32_e32 v80, v196, v180
	v_add_f32_e32 v180, v201, v202
	v_fmac_f32_e32 v180, v80, v200
	s_add_i32 s6, s6, 2
	s_and_b64 vcc, exec, s[4:5]
	s_waitcnt lgkmcnt(0)
	s_barrier
	s_cbranch_vccnz .LBB0_440
	v_mov_b32_e32 v196, v199
	s_branch .LBB0_423

.LBB0_805:
	s_lshl_b32 s0, s39, 10
	s_and_b32 s6, s0, 0x800000
	s_lshl_b32 s0, s43, 1
	s_and_b32 s65, s0, 0x300
	s_lshl_b32 s0, s2, 11
	s_lshl_b32 s1, s2, 4
	s_and_b32 s0, s0, 0x2000
	s_and_b32 s1, s1, 0xffffff80
	s_add_i32 s1, s0, s1
	v_or_b32_e32 v171, s1, v170
	v_or_b32_e32 v0, v171, v169
	v_ashrrev_i32_e32 v1, 31, v0
	s_lshl_b32 s1, s2, 7
	v_lshlrev_b64 v[0:1], 10, v[0:1]
	s_and_b32 s64, s1, 0x180
	v_lshl_add_u64 v[0:1], s[86:87], 0, v[0:1]
	s_lshl_b32 s4, s64, 1
	s_mov_b32 s5, s7
	v_lshl_add_u64 v[0:1], v[0:1], 0, s[4:5]
	s_lshl_b32 s5, s0, 10
	s_add_u32 s0, s33, s5
	s_addc_u32 s1, s34, 0
	s_add_u32 s0, s0, s4
	v_mov_b32_e32 v174, v168
	v_lshl_add_u64 v[0:1], v[160:161], 1, v[0:1]
	s_addc_u32 s1, s1, 0
	v_lshl_add_u64 v[0:1], v[0:1], 0, v[162:163]
	v_ashrrev_i32_e32 v16, 4, v174
	s_add_u32 s5, s35, s5
	v_lshlrev_b32_e32 v20, 3, v174
	v_add_u32_e32 v18, 32, v16
	s_addc_u32 s16, s38, 0
	global_load_dwordx4 v[124:127], v[0:1], off
	global_load_dwordx4 v[120:123], v[0:1], off offset:32
	global_load_dwordx4 v[116:119], v[0:1], off offset:64
	global_load_dwordx4 v[112:115], v[0:1], off offset:96
	v_and_b32_e32 v0, 0x78, v20
	v_ashrrev_i32_e32 v17, 31, v16
	v_ashrrev_i32_e32 v19, 31, v18
	s_add_u32 s4, s5, s4
	v_lshlrev_b32_e32 v21, 1, v0
	v_lshlrev_b64 v[48:49], 10, v[16:17]
	v_lshlrev_b64 v[12:13], 10, v[18:19]
	s_addc_u32 s5, s16, 0
	v_or_b32_e32 v50, v48, v21
	v_mov_b32_e32 v51, v49
	v_or_b32_e32 v12, v12, v21
	v_lshl_add_u64 v[0:1], s[4:5], 0, v[50:51]
	v_lshl_add_u64 v[4:5], s[4:5], 0, v[12:13]
	s_barrier
	global_load_dwordx4 v[0:3], v[0:1], off
	s_nop 0
	global_load_dwordx4 v[4:7], v[4:5], off
	v_lshl_add_u64 v[8:9], s[0:1], 0, v[50:51]
	global_load_dwordx4 v[8:11], v[8:9], off
	v_lshl_add_u64 v[12:13], s[0:1], 0, v[12:13]
	global_load_dwordx4 v[12:15], v[12:13], off
	v_and_b32_e32 v22, 0xfffff0, v16
	v_lshlrev_b32_e32 v23, 1, v16
	v_lshrrev_b32_e32 v24, 1, v16
	v_and_b32_e32 v25, 3, v16
	v_and_or_b32 v22, v23, 8, v22
	v_and_or_b32 v23, v24, 4, v25
	v_and_b32_e32 v24, 0xfffff0, v18
	v_lshlrev_b32_e32 v25, 1, v18
	v_and_b32_e32 v17, 0x70, v174
	v_bfe_u32 v20, v20, 5, 2
	v_lshlrev_b32_e32 v16, 8, v16
	v_lshrrev_b32_e32 v22, 1, v22
	v_and_or_b32 v24, v25, 8, v24
	v_bitop3_b32 v183, v21, v16, v17 bitop3:0xde
	v_or_b32_e32 v16, v22, v20
	v_lshrrev_b32_e32 v22, 1, v24
	v_lshlrev_b32_e32 v23, 6, v23
	v_and_b32_e32 v26, 48, v21
	v_lshlrev_b32_e32 v16, 9, v16
	v_or_b32_e32 v20, v22, v20
	v_or3_b32 v184, v16, v23, v26
	v_lshlrev_b32_e32 v16, 9, v20
	v_bfe_u32 v172, v174, 5, 1
	v_ashrrev_i32_e32 v175, 8, v174
	v_lshlrev_b32_e32 v52, 4, v174
	v_or3_b32 v186, v16, v23, v26
	v_add_u32_e32 v84, 16, v184
	v_and_b32_e32 v173, 31, v174
	v_lshlrev_b32_e32 v19, 7, v175
	v_add_u32_e32 v24, 16, v183
	v_add_u32_e32 v85, 16, v186
	s_waitcnt vmcnt(0)
	v_lshlrev_b32_e32 v176, 4, v172
	v_lshlrev_b32_e32 v190, 8, v173
	v_and_b32_e32 v86, 63, v174
	v_lshl_add_u64 v[60:61], v[50:51], 0, s[14:15]
	v_lshl_add_u64 v[64:65], v[50:51], 0, s[36:37]
	v_lshl_add_u64 v[56:57], s[4:5], 0, v[64:65]
	v_lshl_add_u64 v[64:65], s[0:1], 0, v[64:65]
	s_cmp_lg_u32 16, -1
	s_cselect_b32 s16, 16, 0
	s_mov_b32 s17, s7
	s_mov_b32 s18, s7
	s_mov_b32 s19, s7
	s_mov_b32 s20, s7
	s_waitcnt vmcnt(3)
	ds_write_b128 v84, v[0:3]
	s_waitcnt vmcnt(2)
	ds_write_b128 v85, v[4:7]
	s_waitcnt vmcnt(1)
	ds_write_b128 v24, v[8:11] offset:49152
	v_and_b32_e32 v8, 0x70, v52
	v_lshlrev_b32_e32 v0, 8, v18
	v_bitop3_b32 v182, v176, v8, v19 bitop3:0x36
	v_bitop3_b32 v188, v21, v0, v17 bitop3:0xde
	v_add_u32_e32 v185, v182, v190
	v_add_u32_e32 v0, 16, v188
	v_add_u32_e32 v4, 16, v185
	s_waitcnt vmcnt(0)
	ds_write_b128 v0, v[12:15] offset:49152
	s_waitcnt lgkmcnt(0)
	s_barrier
	ds_read_b128 v[0:3], v4 offset:49152
	ds_read_b128 v[4:7], v4 offset:57344
	v_or_b32_e32 v9, v176, v19
	v_bitop3_b32 v187, v9, v8, 32 bitop3:0x36
	v_add_u32_e32 v189, v187, v190
	s_waitcnt lgkmcnt(0)
	v_mfma_f32_32x32x16_bf16 v[16:31], v[4:7], v[124:127], 0
	v_add_u32_e32 v4, 16, v189
	v_bitop3_b32 v193, v9, v8, s3 bitop3:0x36
	v_bitop3_b32 v191, v9, v8, 64 bitop3:0x36
	v_add_u32_e32 v194, v193, v190
	v_add_u32_e32 v192, v191, v190
	v_add_u32_e32 v8, 16, v194
	v_and_b32_e32 v5, 0x3fffffc0, v174
	v_mfma_f32_32x32x16_bf16 v[32:47], v[0:3], v[124:127], 0
	ds_read_b128 v[0:3], v4 offset:49152
	v_and_b32_e32 v11, 0xc0, v52
	v_add_u32_e32 v13, 16, v192
	ds_read_b128 v[52:55], v8 offset:57344
	v_lshl_add_u32 v177, v5, 2, s50
	ds_read_b128 v[4:7], v4 offset:57344
	v_lshlrev_b32_e32 v10, 3, v86
	s_waitcnt lgkmcnt(2)
	v_mfma_f32_32x32x16_bf16 v[32:47], v[0:3], v[120:123], v[32:47]
	v_lshlrev_b32_e32 v0, 1, v174
	v_and_b32_e32 v12, 32, v0
	ds_read_b128 v[0:3], v13 offset:49152
	v_and_or_b32 v11, v10, 24, v11
	s_mov_b32 s21, s7
	s_mov_b32 s22, s7
	s_mov_b32 s23, s7
	s_waitcnt lgkmcnt(0)
	v_mfma_f32_32x32x16_bf16 v[32:47], v[0:3], v[116:119], v[32:47]
	ds_read_b128 v[0:3], v8 offset:49152
	s_mov_b32 s24, s7
	s_mov_b32 s25, s7
	s_mov_b32 s26, s7
	s_mov_b32 s27, s7
	s_mov_b32 s28, s7
	s_mov_b32 s29, s7
	v_mfma_f32_32x32x16_bf16 v[16:31], v[4:7], v[120:123], v[16:31]
	v_and_b32_e32 v4, 0x100, v10
	v_or3_b32 v178, v11, v12, v4
	ds_read_b128 v[4:7], v13 offset:57344
	v_add_u32_e32 v181, s16, v178
	s_mov_b32 s16, s7
	s_mov_b32 s30, s7
	s_mov_b32 s31, s7
	s_waitcnt lgkmcnt(0)
	v_mfma_f32_32x32x16_bf16 v[16:31], v[4:7], v[116:119], v[16:31]
	v_lshl_add_u32 v179, v173, 2, v177
	v_mov_b32_e32 v196, 1.0
	v_mov_b32_e32 v180, 0
	v_mfma_f32_32x32x16_bf16 v[32:47], v[0:3], v[112:115], v[32:47]
	v_mov_b64_e32 v[0:1], s[16:17]
	v_mov_b64_e32 v[14:15], s[30:31]
	v_mov_b64_e32 v[2:3], s[18:19]
	v_mov_b64_e32 v[4:5], s[20:21]
	v_mov_b64_e32 v[6:7], s[22:23]
	v_mov_b64_e32 v[8:9], s[24:25]
	v_mov_b64_e32 v[10:11], s[26:27]
	v_mfma_f32_32x32x16_bf16 v[16:31], v[52:55], v[112:115], v[16:31]
	s_nop 3
	v_max_f32_e32 v52, v33, v33
	v_max_f32_e32 v53, v32, v32
	v_max_f32_e32 v52, v53, v52
	v_max3_f32 v52, v52, v34, v35
	v_max3_f32 v52, v52, v36, v37
	v_max3_f32 v52, v52, v38, v39
	v_max3_f32 v52, v52, v40, v41
	v_max3_f32 v52, v52, v42, v43
	v_max3_f32 v52, v52, v44, v45
	v_max3_f32 v66, v52, v46, v47
	v_lshl_add_u64 v[52:53], s[4:5], 0, v[60:61]
	v_lshl_add_u64 v[60:61], s[0:1], 0, v[60:61]
	global_load_dwordx4 v[52:55], v[52:53], off
	s_nop 0
	global_load_dwordx4 v[56:59], v[56:57], off
	v_mov_b64_e32 v[12:13], s[28:29]
	global_load_dwordx4 v[60:63], v[60:61], off
	s_mov_b32 s19, 1
	global_load_dwordx4 v[80:83], v[64:65], off
	v_max3_f32 v64, v66, v16, v17
	v_max3_f32 v64, v64, v18, v19
	v_max3_f32 v64, v64, v20, v21
	v_max3_f32 v64, v64, v22, v23
	v_max3_f32 v64, v64, v24, v25
	v_max3_f32 v64, v64, v26, v27
	v_max3_f32 v64, v64, v28, v29
	v_max3_f32 v70, v64, v30, v31
	v_lshl_add_u64 v[64:65], v[50:51], 0, s[40:41]
	v_lshl_add_u64 v[66:67], s[0:1], 0, v[64:65]
	v_lshl_add_u64 v[50:51], v[50:51], 0, s[44:45]
	v_lshl_add_u64 v[64:65], s[4:5], 0, v[64:65]
	v_lshl_add_u64 v[68:69], s[0:1], 0, v[50:51]
	global_load_dwordx4 v[136:139], v[66:67], off
	global_load_dwordx4 v[128:131], v[68:69], off
	v_lshl_add_u64 v[50:51], s[4:5], 0, v[50:51]
	global_load_dwordx4 v[140:143], v[64:65], off
	global_load_dwordx4 v[132:135], v[50:51], off
	v_mov_b32_e32 v71, v70
	s_nop 1
	v_permlane32_swap_b32_e32 v70, v71
	v_max_f32_e32 v50, v71, v71
	v_max_f32_e32 v51, v70, v70
	v_max_f32_e32 v50, v51, v50
	v_sub_f32_e32 v64, v16, v50
	v_add_u32_e32 v16, s58, v183
	v_sub_f32_e32 v32, v32, v50
	v_sub_f32_e32 v33, v33, v50
	v_sub_f32_e32 v34, v34, v50
	v_sub_f32_e32 v35, v35, v50
	v_sub_f32_e32 v36, v36, v50
	v_sub_f32_e32 v37, v37, v50
	v_sub_f32_e32 v38, v38, v50
	v_sub_f32_e32 v39, v39, v50
	v_sub_f32_e32 v40, v40, v50
	v_sub_f32_e32 v41, v41, v50
	v_sub_f32_e32 v42, v42, v50
	v_sub_f32_e32 v43, v43, v50
	v_sub_f32_e32 v44, v44, v50
	v_sub_f32_e32 v45, v45, v50
	v_sub_f32_e32 v46, v46, v50
	v_sub_f32_e32 v47, v47, v50
	v_sub_f32_e32 v66, v18, v50
	s_waitcnt vmcnt(4)
	s_waitcnt vmcnt(7)
	ds_write_b128 v84, v[52:55] offset:16384
	s_waitcnt vmcnt(6)
	ds_write_b128 v85, v[56:59] offset:16384
	v_and_b32_e32 v18, 15, v174
	s_waitcnt vmcnt(5)
	ds_write_b128 v16, v[60:63]
	v_add_u32_e32 v16, s58, v188
	v_sub_f32_e32 v65, v17, v50
	v_exp_f32_e32 v152, v32
	v_exp_f32_e32 v153, v33
	v_exp_f32_e32 v154, v34
	v_exp_f32_e32 v155, v35
	v_exp_f32_e32 v156, v36
	v_exp_f32_e32 v157, v37
	v_exp_f32_e32 v158, v38
	v_exp_f32_e32 v159, v39
	v_exp_f32_e32 v144, v40
	v_exp_f32_e32 v145, v41
	v_exp_f32_e32 v146, v42
	v_exp_f32_e32 v147, v43
	v_exp_f32_e32 v148, v44
	v_exp_f32_e32 v149, v45
	v_exp_f32_e32 v150, v46
	v_exp_f32_e32 v151, v47
	s_waitcnt vmcnt(4)
	ds_write_b128 v16, v[80:83]
	v_lshl_add_u64 v[16:17], s[6:7], 0, v[48:49]
	v_lshlrev_b32_e32 v18, 4, v18
	v_or3_b32 v16, v16, s65, v18
	v_add_f32_e32 v195, 0, v50
	v_sub_f32_e32 v79, v31, v50
	v_sub_f32_e32 v78, v30, v50
	v_sub_f32_e32 v77, v29, v50
	v_sub_f32_e32 v76, v28, v50
	v_sub_f32_e32 v75, v27, v50
	v_sub_f32_e32 v74, v26, v50
	v_sub_f32_e32 v73, v25, v50
	v_sub_f32_e32 v72, v24, v50
	v_sub_f32_e32 v71, v23, v50
	v_sub_f32_e32 v70, v22, v50
	v_sub_f32_e32 v69, v21, v50
	v_sub_f32_e32 v68, v20, v50
	v_sub_f32_e32 v67, v19, v50
	v_lshl_add_u64 v[166:167], s[12:13], 0, v[16:17]
	v_mov_b64_e32 v[62:63], v[14:15]
	v_mov_b64_e32 v[46:47], v[14:15]
	v_mov_b64_e32 v[30:31], v[14:15]
	v_cmp_gt_u32_e64 s[0:1], 32, v86
	v_mov_b64_e32 v[60:61], v[12:13]
	v_mov_b64_e32 v[58:59], v[10:11]
	v_mov_b64_e32 v[56:57], v[8:9]
	v_mov_b64_e32 v[54:55], v[6:7]
	v_mov_b64_e32 v[52:53], v[4:5]
	v_mov_b64_e32 v[50:51], v[2:3]
	v_mov_b64_e32 v[48:49], v[0:1]
	v_mov_b64_e32 v[44:45], v[12:13]
	v_mov_b64_e32 v[42:43], v[10:11]
	v_mov_b64_e32 v[40:41], v[8:9]
	v_mov_b64_e32 v[38:39], v[6:7]
	v_mov_b64_e32 v[36:37], v[4:5]
	v_mov_b64_e32 v[34:35], v[2:3]
	v_mov_b64_e32 v[32:33], v[0:1]
	v_mov_b64_e32 v[28:29], v[12:13]
	v_mov_b64_e32 v[26:27], v[10:11]
	v_mov_b64_e32 v[24:25], v[8:9]
	v_mov_b64_e32 v[22:23], v[6:7]
	v_mov_b64_e32 v[20:21], v[4:5]
	v_mov_b64_e32 v[18:19], v[2:3]
	v_mov_b64_e32 v[16:17], v[0:1]
	s_mov_b32 s6, 1
	s_mov_b32 s18, 0
	s_waitcnt lgkmcnt(0)
	s_barrier
	v_add_co_u32_e32 v242, vcc, s61, v166
	s_nop 1
	v_addc_co_u32_e32 v243, vcc, -1, v167, vcc
	s_nop 0
	v_readfirstlane_b32 s98, v242
	v_readfirstlane_b32 s99, v243
	s_nop 1
	v_subrev_u32_e32 v242, s98, v242
	v_add_u32_e32 v243, 0x8000, v242
	v_add_u32_e32 v244, 0x1000000, v242
	v_add_u32_e32 v245, 0x1008000, v242
